# prologue: x->bf16 rows with all eight rows' loads in flight per wave (fast path at this grid), DPP row reduction; census sum de-serialised
# speedup vs baseline: 1.0093x; 1.0093x over previous
.LBB0_61:
	s_cmpk_gt_i32 s38, 0x3fff
	v_readlane_b32 s86, v251, 40
	s_cbranch_scc1 .LBB0_66
	s_ashr_i32 s39, s38, 31
	v_ashrrev_i32_e32 v17, 31, v16
	v_lshlrev_b32_e32 v2, 2, v16
	s_lshl_b64 s[6:7], s[38:39], 6
	v_xor_b32_e32 v8, 4, v2
	v_xor_b32_e32 v9, 8, v2
	v_xor_b32_e32 v10, 16, v2
	v_xor_b32_e32 v11, 32, v2
	v_xor_b32_e32 v12, 64, v2
	v_xor_b32_e32 v13, 0x80, v2
	v_lshl_add_u64 v[2:3], v[16:17], 2, s[6:7]
	s_mov_b64 s[6:7], 0x22300000
	s_ashr_i32 s41, s40, 31
	s_lshl_b64 s[8:9], s[38:39], 11
	v_lshl_add_u64 v[2:3], v[2:3], 0, s[6:7]
	s_lshl_b64 s[6:7], s[40:41], 6
	v_lshl_add_u64 v[4:5], v[16:17], 3, s[8:9]
	s_lshl_b64 s[8:9], s[40:41], 11
	s_lshl_b64 s[10:11], s[38:39], 12
	s_add_u32 s10, s16, s10
	s_addc_u32 s11, s17, s11
	v_lshl_add_u64 v[6:7], v[16:17], 4, s[10:11]
	s_mov_b64 s[10:11], 0x800
	v_cmp_gt_i32_e64 s[0:1], 16, v16
	v_cmp_eq_u32_e64 s[4:5], 0, v16
	v_lshl_add_u64 v[6:7], v[6:7], 0, s[10:11]
	s_lshl_b64 s[10:11], s[40:41], 12
	s_mov_b32 s3, s38
	s_cmpk_lg_i32 s40, 0x800
	s_cbranch_scc1 .Lx_generic
	global_load_dwordx4 v[60:63], v[6:7], off offset:-2048 nt
	global_load_dwordx4 v[64:67], v[6:7], off offset:-1024 nt
	global_load_dwordx4 v[68:71], v[6:7], off nt
	global_load_dwordx4 v[72:75], v[6:7], off offset:1024 nt
	v_lshl_add_u64 v[6:7], v[6:7], 0, s[10:11]
	global_load_dwordx4 v[76:79], v[6:7], off offset:-2048 nt
	global_load_dwordx4 v[80:83], v[6:7], off offset:-1024 nt
	global_load_dwordx4 v[84:87], v[6:7], off nt
	global_load_dwordx4 v[88:91], v[6:7], off offset:1024 nt
	v_lshl_add_u64 v[6:7], v[6:7], 0, s[10:11]
	global_load_dwordx4 v[92:95], v[6:7], off offset:-2048 nt
	global_load_dwordx4 v[96:99], v[6:7], off offset:-1024 nt
	global_load_dwordx4 v[100:103], v[6:7], off nt
	global_load_dwordx4 v[104:107], v[6:7], off offset:1024 nt
	v_lshl_add_u64 v[6:7], v[6:7], 0, s[10:11]
	global_load_dwordx4 v[108:111], v[6:7], off offset:-2048 nt
	global_load_dwordx4 v[112:115], v[6:7], off offset:-1024 nt
	global_load_dwordx4 v[116:119], v[6:7], off nt
	global_load_dwordx4 v[120:123], v[6:7], off offset:1024 nt
	v_lshl_add_u64 v[6:7], v[6:7], 0, s[10:11]
	global_load_dwordx4 v[124:127], v[6:7], off offset:-2048 nt
	global_load_dwordx4 v[128:131], v[6:7], off offset:-1024 nt
	global_load_dwordx4 v[132:135], v[6:7], off nt
	global_load_dwordx4 v[136:139], v[6:7], off offset:1024 nt
	v_lshl_add_u64 v[6:7], v[6:7], 0, s[10:11]
	global_load_dwordx4 v[140:143], v[6:7], off offset:-2048 nt
	global_load_dwordx4 v[144:147], v[6:7], off offset:-1024 nt
	global_load_dwordx4 v[148:151], v[6:7], off nt
	global_load_dwordx4 v[152:155], v[6:7], off offset:1024 nt
	v_lshl_add_u64 v[6:7], v[6:7], 0, s[10:11]
	global_load_dwordx4 v[156:159], v[6:7], off offset:-2048 nt
	global_load_dwordx4 v[160:163], v[6:7], off offset:-1024 nt
	global_load_dwordx4 v[164:167], v[6:7], off nt
	global_load_dwordx4 v[168:171], v[6:7], off offset:1024 nt
	v_lshl_add_u64 v[6:7], v[6:7], 0, s[10:11]
	global_load_dwordx4 v[172:175], v[6:7], off offset:-2048 nt
	global_load_dwordx4 v[176:179], v[6:7], off offset:-1024 nt
	global_load_dwordx4 v[180:183], v[6:7], off nt
	global_load_dwordx4 v[184:187], v[6:7], off offset:1024 nt
	v_lshl_add_u64 v[20:21], s[46:47], 0, v[4:5]
	v_add_co_u32_e32 v20, vcc, 0xe200000, v20
	s_waitcnt vmcnt(31)
	v_cvt_pk_bf16_f32 v22, v60, v61
	v_addc_co_u32_e32 v21, vcc, 0, v21, vcc
	v_cvt_pk_bf16_f32 v23, v62, v63
	global_store_dwordx2 v[20:21], v[22:23], off
	v_lshlrev_b32_e32 v28, 16, v22
	v_and_b32_e32 v22, 0xffff0000, v22
	v_lshlrev_b32_e32 v29, 16, v23
	v_and_b32_e32 v23, 0xffff0000, v23
	v_mul_f32_e32 v22, v22, v22
	v_mul_f32_e32 v23, v23, v23
	v_fmac_f32_e32 v22, v28, v28
	v_fmac_f32_e32 v23, v29, v29
	v_add_f32_e32 v22, v22, v23
	s_waitcnt vmcnt(31)
	v_cvt_pk_bf16_f32 v24, v64, v65
	v_cvt_pk_bf16_f32 v25, v66, v67
	global_store_dwordx2 v[20:21], v[24:25], off offset:512
	v_lshlrev_b32_e32 v23, 16, v24
	v_and_b32_e32 v24, 0xffff0000, v24
	v_lshlrev_b32_e32 v28, 16, v25
	v_and_b32_e32 v25, 0xffff0000, v25
	v_mul_f32_e32 v24, v24, v24
	v_mul_f32_e32 v25, v25, v25
	v_fmac_f32_e32 v24, v23, v23
	v_fmac_f32_e32 v25, v28, v28
	v_add_f32_e32 v23, v24, v25
	v_add_f32_e32 v22, v22, v23
	s_waitcnt vmcnt(31)
	v_cvt_pk_bf16_f32 v26, v68, v69
	v_cvt_pk_bf16_f32 v27, v70, v71
	global_store_dwordx2 v[20:21], v[26:27], off offset:1024
	v_lshlrev_b32_e32 v23, 16, v26
	v_and_b32_e32 v24, 0xffff0000, v26
	v_and_b32_e32 v26, 0xffff0000, v27
	v_lshlrev_b32_e32 v25, 16, v27
	v_mul_f32_e32 v24, v24, v24
	v_mul_f32_e32 v26, v26, v26
	v_fmac_f32_e32 v24, v23, v23
	v_fmac_f32_e32 v26, v25, v25
	v_add_f32_e32 v23, v24, v26
	v_add_f32_e32 v24, v22, v23
	s_waitcnt vmcnt(31)
	v_cvt_pk_bf16_f32 v22, v72, v73
	v_cvt_pk_bf16_f32 v23, v74, v75
	v_and_b32_e32 v61, 0xffff0000, v22
	v_and_b32_e32 v63, 0xffff0000, v23
	v_lshlrev_b32_e32 v60, 16, v22
	v_lshlrev_b32_e32 v62, 16, v23
	v_mul_f32_e32 v61, v61, v61
	v_mul_f32_e32 v63, v63, v63
	v_fmac_f32_e32 v61, v60, v60
	v_fmac_f32_e32 v63, v62, v62
	v_add_f32_e32 v60, v61, v63
	v_add_f32_e32 v60, v24, v60
	s_nop 1
	v_add_f32_dpp v61, v60, v60 quad_perm:[1,0,3,2] row_mask:0xf bank_mask:0xf
	s_nop 1
	v_add_f32_dpp v60, v61, v61 quad_perm:[2,3,0,1] row_mask:0xf bank_mask:0xf
	s_nop 1
	v_add_f32_dpp v61, v60, v60 row_half_mirror row_mask:0xf bank_mask:0xf
	s_nop 1
	v_add_f32_dpp v60, v61, v61 row_ror:8 row_mask:0xf bank_mask:0xf
	v_mov_b32_e32 v61, v60
	s_nop 1
	v_permlane16_swap_b32_e32 v61, v60
	v_add_f32_e32 v60, v61, v60
	v_mov_b32_e32 v61, v60
	s_nop 1
	v_permlane32_swap_b32_e32 v61, v60
	v_add_f32_e32 v60, v61, v60
	global_store_dwordx2 v[20:21], v[22:23], off offset:1536
	s_and_saveexec_b64 s[12:13], s[0:1]
	v_lshl_add_u64 v[62:63], s[46:47], 0, v[2:3]
	v_cndmask_b32_e64 v60, 0, v60, s[4:5]
	global_store_dword v[62:63], v60, off
	s_or_b64 exec, exec, s[12:13]
	v_lshl_add_u64 v[2:3], v[2:3], 0, s[6:7]
	v_lshl_add_u64 v[4:5], v[4:5], 0, s[8:9]
	v_lshl_add_u64 v[20:21], s[46:47], 0, v[4:5]
	v_add_co_u32_e32 v20, vcc, 0xe200000, v20
	s_waitcnt vmcnt(32)
	v_cvt_pk_bf16_f32 v22, v76, v77
	v_addc_co_u32_e32 v21, vcc, 0, v21, vcc
	v_cvt_pk_bf16_f32 v23, v78, v79
	global_store_dwordx2 v[20:21], v[22:23], off
	v_lshlrev_b32_e32 v28, 16, v22
	v_and_b32_e32 v22, 0xffff0000, v22
	v_lshlrev_b32_e32 v29, 16, v23
	v_and_b32_e32 v23, 0xffff0000, v23
	v_mul_f32_e32 v22, v22, v22
	v_mul_f32_e32 v23, v23, v23
	v_fmac_f32_e32 v22, v28, v28
	v_fmac_f32_e32 v23, v29, v29
	v_add_f32_e32 v22, v22, v23
	s_waitcnt vmcnt(32)
	v_cvt_pk_bf16_f32 v24, v80, v81
	v_cvt_pk_bf16_f32 v25, v82, v83
	global_store_dwordx2 v[20:21], v[24:25], off offset:512
	v_lshlrev_b32_e32 v23, 16, v24
	v_and_b32_e32 v24, 0xffff0000, v24
	v_lshlrev_b32_e32 v28, 16, v25
	v_and_b32_e32 v25, 0xffff0000, v25
	v_mul_f32_e32 v24, v24, v24
	v_mul_f32_e32 v25, v25, v25
	v_fmac_f32_e32 v24, v23, v23
	v_fmac_f32_e32 v25, v28, v28
	v_add_f32_e32 v23, v24, v25
	v_add_f32_e32 v22, v22, v23
	s_waitcnt vmcnt(32)
	v_cvt_pk_bf16_f32 v26, v84, v85
	v_cvt_pk_bf16_f32 v27, v86, v87
	global_store_dwordx2 v[20:21], v[26:27], off offset:1024
	v_lshlrev_b32_e32 v23, 16, v26
	v_and_b32_e32 v24, 0xffff0000, v26
	v_and_b32_e32 v26, 0xffff0000, v27
	v_lshlrev_b32_e32 v25, 16, v27
	v_mul_f32_e32 v24, v24, v24
	v_mul_f32_e32 v26, v26, v26
	v_fmac_f32_e32 v24, v23, v23
	v_fmac_f32_e32 v26, v25, v25
	v_add_f32_e32 v23, v24, v26
	v_add_f32_e32 v24, v22, v23
	s_waitcnt vmcnt(32)
	v_cvt_pk_bf16_f32 v22, v88, v89
	v_cvt_pk_bf16_f32 v23, v90, v91
	v_and_b32_e32 v77, 0xffff0000, v22
	v_and_b32_e32 v79, 0xffff0000, v23
	v_lshlrev_b32_e32 v76, 16, v22
	v_lshlrev_b32_e32 v78, 16, v23
	v_mul_f32_e32 v77, v77, v77
	v_mul_f32_e32 v79, v79, v79
	v_fmac_f32_e32 v77, v76, v76
	v_fmac_f32_e32 v79, v78, v78
	v_add_f32_e32 v76, v77, v79
	v_add_f32_e32 v76, v24, v76
	s_nop 1
	v_add_f32_dpp v77, v76, v76 quad_perm:[1,0,3,2] row_mask:0xf bank_mask:0xf
	s_nop 1
	v_add_f32_dpp v76, v77, v77 quad_perm:[2,3,0,1] row_mask:0xf bank_mask:0xf
	s_nop 1
	v_add_f32_dpp v77, v76, v76 row_half_mirror row_mask:0xf bank_mask:0xf
	s_nop 1
	v_add_f32_dpp v76, v77, v77 row_ror:8 row_mask:0xf bank_mask:0xf
	v_mov_b32_e32 v77, v76
	s_nop 1
	v_permlane16_swap_b32_e32 v77, v76
	v_add_f32_e32 v76, v77, v76
	v_mov_b32_e32 v77, v76
	s_nop 1
	v_permlane32_swap_b32_e32 v77, v76
	v_add_f32_e32 v76, v77, v76
	global_store_dwordx2 v[20:21], v[22:23], off offset:1536
	s_and_saveexec_b64 s[12:13], s[0:1]
	v_lshl_add_u64 v[78:79], s[46:47], 0, v[2:3]
	v_cndmask_b32_e64 v76, 0, v76, s[4:5]
	global_store_dword v[78:79], v76, off
	s_or_b64 exec, exec, s[12:13]
	v_lshl_add_u64 v[2:3], v[2:3], 0, s[6:7]
	v_lshl_add_u64 v[4:5], v[4:5], 0, s[8:9]
	v_lshl_add_u64 v[20:21], s[46:47], 0, v[4:5]
	v_add_co_u32_e32 v20, vcc, 0xe200000, v20
	s_waitcnt vmcnt(33)
	v_cvt_pk_bf16_f32 v22, v92, v93
	v_addc_co_u32_e32 v21, vcc, 0, v21, vcc
	v_cvt_pk_bf16_f32 v23, v94, v95
	global_store_dwordx2 v[20:21], v[22:23], off
	v_lshlrev_b32_e32 v28, 16, v22
	v_and_b32_e32 v22, 0xffff0000, v22
	v_lshlrev_b32_e32 v29, 16, v23
	v_and_b32_e32 v23, 0xffff0000, v23
	v_mul_f32_e32 v22, v22, v22
	v_mul_f32_e32 v23, v23, v23
	v_fmac_f32_e32 v22, v28, v28
	v_fmac_f32_e32 v23, v29, v29
	v_add_f32_e32 v22, v22, v23
	s_waitcnt vmcnt(33)
	v_cvt_pk_bf16_f32 v24, v96, v97
	v_cvt_pk_bf16_f32 v25, v98, v99
	global_store_dwordx2 v[20:21], v[24:25], off offset:512
	v_lshlrev_b32_e32 v23, 16, v24
	v_and_b32_e32 v24, 0xffff0000, v24
	v_lshlrev_b32_e32 v28, 16, v25
	v_and_b32_e32 v25, 0xffff0000, v25
	v_mul_f32_e32 v24, v24, v24
	v_mul_f32_e32 v25, v25, v25
	v_fmac_f32_e32 v24, v23, v23
	v_fmac_f32_e32 v25, v28, v28
	v_add_f32_e32 v23, v24, v25
	v_add_f32_e32 v22, v22, v23
	s_waitcnt vmcnt(33)
	v_cvt_pk_bf16_f32 v26, v100, v101
	v_cvt_pk_bf16_f32 v27, v102, v103
	global_store_dwordx2 v[20:21], v[26:27], off offset:1024
	v_lshlrev_b32_e32 v23, 16, v26
	v_and_b32_e32 v24, 0xffff0000, v26
	v_and_b32_e32 v26, 0xffff0000, v27
	v_lshlrev_b32_e32 v25, 16, v27
	v_mul_f32_e32 v24, v24, v24
	v_mul_f32_e32 v26, v26, v26
	v_fmac_f32_e32 v24, v23, v23
	v_fmac_f32_e32 v26, v25, v25
	v_add_f32_e32 v23, v24, v26
	v_add_f32_e32 v24, v22, v23
	s_waitcnt vmcnt(33)
	v_cvt_pk_bf16_f32 v22, v104, v105
	v_cvt_pk_bf16_f32 v23, v106, v107
	v_and_b32_e32 v93, 0xffff0000, v22
	v_and_b32_e32 v95, 0xffff0000, v23
	v_lshlrev_b32_e32 v92, 16, v22
	v_lshlrev_b32_e32 v94, 16, v23
	v_mul_f32_e32 v93, v93, v93
	v_mul_f32_e32 v95, v95, v95
	v_fmac_f32_e32 v93, v92, v92
	v_fmac_f32_e32 v95, v94, v94
	v_add_f32_e32 v92, v93, v95
	v_add_f32_e32 v92, v24, v92
	s_nop 1
	v_add_f32_dpp v93, v92, v92 quad_perm:[1,0,3,2] row_mask:0xf bank_mask:0xf
	s_nop 1
	v_add_f32_dpp v92, v93, v93 quad_perm:[2,3,0,1] row_mask:0xf bank_mask:0xf
	s_nop 1
	v_add_f32_dpp v93, v92, v92 row_half_mirror row_mask:0xf bank_mask:0xf
	s_nop 1
	v_add_f32_dpp v92, v93, v93 row_ror:8 row_mask:0xf bank_mask:0xf
	v_mov_b32_e32 v93, v92
	s_nop 1
	v_permlane16_swap_b32_e32 v93, v92
	v_add_f32_e32 v92, v93, v92
	v_mov_b32_e32 v93, v92
	s_nop 1
	v_permlane32_swap_b32_e32 v93, v92
	v_add_f32_e32 v92, v93, v92
	global_store_dwordx2 v[20:21], v[22:23], off offset:1536
	s_and_saveexec_b64 s[12:13], s[0:1]
	v_lshl_add_u64 v[94:95], s[46:47], 0, v[2:3]
	v_cndmask_b32_e64 v92, 0, v92, s[4:5]
	global_store_dword v[94:95], v92, off
	s_or_b64 exec, exec, s[12:13]
	v_lshl_add_u64 v[2:3], v[2:3], 0, s[6:7]
	v_lshl_add_u64 v[4:5], v[4:5], 0, s[8:9]
	v_lshl_add_u64 v[20:21], s[46:47], 0, v[4:5]
	v_add_co_u32_e32 v20, vcc, 0xe200000, v20
	s_waitcnt vmcnt(34)
	v_cvt_pk_bf16_f32 v22, v108, v109
	v_addc_co_u32_e32 v21, vcc, 0, v21, vcc
	v_cvt_pk_bf16_f32 v23, v110, v111
	global_store_dwordx2 v[20:21], v[22:23], off
	v_lshlrev_b32_e32 v28, 16, v22
	v_and_b32_e32 v22, 0xffff0000, v22
	v_lshlrev_b32_e32 v29, 16, v23
	v_and_b32_e32 v23, 0xffff0000, v23
	v_mul_f32_e32 v22, v22, v22
	v_mul_f32_e32 v23, v23, v23
	v_fmac_f32_e32 v22, v28, v28
	v_fmac_f32_e32 v23, v29, v29
	v_add_f32_e32 v22, v22, v23
	s_waitcnt vmcnt(34)
	v_cvt_pk_bf16_f32 v24, v112, v113
	v_cvt_pk_bf16_f32 v25, v114, v115
	global_store_dwordx2 v[20:21], v[24:25], off offset:512
	v_lshlrev_b32_e32 v23, 16, v24
	v_and_b32_e32 v24, 0xffff0000, v24
	v_lshlrev_b32_e32 v28, 16, v25
	v_and_b32_e32 v25, 0xffff0000, v25
	v_mul_f32_e32 v24, v24, v24
	v_mul_f32_e32 v25, v25, v25
	v_fmac_f32_e32 v24, v23, v23
	v_fmac_f32_e32 v25, v28, v28
	v_add_f32_e32 v23, v24, v25
	v_add_f32_e32 v22, v22, v23
	s_waitcnt vmcnt(34)
	v_cvt_pk_bf16_f32 v26, v116, v117
	v_cvt_pk_bf16_f32 v27, v118, v119
	global_store_dwordx2 v[20:21], v[26:27], off offset:1024
	v_lshlrev_b32_e32 v23, 16, v26
	v_and_b32_e32 v24, 0xffff0000, v26
	v_and_b32_e32 v26, 0xffff0000, v27
	v_lshlrev_b32_e32 v25, 16, v27
	v_mul_f32_e32 v24, v24, v24
	v_mul_f32_e32 v26, v26, v26
	v_fmac_f32_e32 v24, v23, v23
	v_fmac_f32_e32 v26, v25, v25
	v_add_f32_e32 v23, v24, v26
	v_add_f32_e32 v24, v22, v23
	s_waitcnt vmcnt(34)
	v_cvt_pk_bf16_f32 v22, v120, v121
	v_cvt_pk_bf16_f32 v23, v122, v123
	v_and_b32_e32 v109, 0xffff0000, v22
	v_and_b32_e32 v111, 0xffff0000, v23
	v_lshlrev_b32_e32 v108, 16, v22
	v_lshlrev_b32_e32 v110, 16, v23
	v_mul_f32_e32 v109, v109, v109
	v_mul_f32_e32 v111, v111, v111
	v_fmac_f32_e32 v109, v108, v108
	v_fmac_f32_e32 v111, v110, v110
	v_add_f32_e32 v108, v109, v111
	v_add_f32_e32 v108, v24, v108
	s_nop 1
	v_add_f32_dpp v109, v108, v108 quad_perm:[1,0,3,2] row_mask:0xf bank_mask:0xf
	s_nop 1
	v_add_f32_dpp v108, v109, v109 quad_perm:[2,3,0,1] row_mask:0xf bank_mask:0xf
	s_nop 1
	v_add_f32_dpp v109, v108, v108 row_half_mirror row_mask:0xf bank_mask:0xf
	s_nop 1
	v_add_f32_dpp v108, v109, v109 row_ror:8 row_mask:0xf bank_mask:0xf
	v_mov_b32_e32 v109, v108
	s_nop 1
	v_permlane16_swap_b32_e32 v109, v108
	v_add_f32_e32 v108, v109, v108
	v_mov_b32_e32 v109, v108
	s_nop 1
	v_permlane32_swap_b32_e32 v109, v108
	v_add_f32_e32 v108, v109, v108
	global_store_dwordx2 v[20:21], v[22:23], off offset:1536
	s_and_saveexec_b64 s[12:13], s[0:1]
	v_lshl_add_u64 v[110:111], s[46:47], 0, v[2:3]
	v_cndmask_b32_e64 v108, 0, v108, s[4:5]
	global_store_dword v[110:111], v108, off
	s_or_b64 exec, exec, s[12:13]
	v_lshl_add_u64 v[2:3], v[2:3], 0, s[6:7]
	v_lshl_add_u64 v[4:5], v[4:5], 0, s[8:9]
	v_lshl_add_u64 v[20:21], s[46:47], 0, v[4:5]
	v_add_co_u32_e32 v20, vcc, 0xe200000, v20
	s_waitcnt vmcnt(35)
	v_cvt_pk_bf16_f32 v22, v124, v125
	v_addc_co_u32_e32 v21, vcc, 0, v21, vcc
	v_cvt_pk_bf16_f32 v23, v126, v127
	global_store_dwordx2 v[20:21], v[22:23], off
	v_lshlrev_b32_e32 v28, 16, v22
	v_and_b32_e32 v22, 0xffff0000, v22
	v_lshlrev_b32_e32 v29, 16, v23
	v_and_b32_e32 v23, 0xffff0000, v23
	v_mul_f32_e32 v22, v22, v22
	v_mul_f32_e32 v23, v23, v23
	v_fmac_f32_e32 v22, v28, v28
	v_fmac_f32_e32 v23, v29, v29
	v_add_f32_e32 v22, v22, v23
	s_waitcnt vmcnt(35)
	v_cvt_pk_bf16_f32 v24, v128, v129
	v_cvt_pk_bf16_f32 v25, v130, v131
	global_store_dwordx2 v[20:21], v[24:25], off offset:512
	v_lshlrev_b32_e32 v23, 16, v24
	v_and_b32_e32 v24, 0xffff0000, v24
	v_lshlrev_b32_e32 v28, 16, v25
	v_and_b32_e32 v25, 0xffff0000, v25
	v_mul_f32_e32 v24, v24, v24
	v_mul_f32_e32 v25, v25, v25
	v_fmac_f32_e32 v24, v23, v23
	v_fmac_f32_e32 v25, v28, v28
	v_add_f32_e32 v23, v24, v25
	v_add_f32_e32 v22, v22, v23
	s_waitcnt vmcnt(35)
	v_cvt_pk_bf16_f32 v26, v132, v133
	v_cvt_pk_bf16_f32 v27, v134, v135
	global_store_dwordx2 v[20:21], v[26:27], off offset:1024
	v_lshlrev_b32_e32 v23, 16, v26
	v_and_b32_e32 v24, 0xffff0000, v26
	v_and_b32_e32 v26, 0xffff0000, v27
	v_lshlrev_b32_e32 v25, 16, v27
	v_mul_f32_e32 v24, v24, v24
	v_mul_f32_e32 v26, v26, v26
	v_fmac_f32_e32 v24, v23, v23
	v_fmac_f32_e32 v26, v25, v25
	v_add_f32_e32 v23, v24, v26
	v_add_f32_e32 v24, v22, v23
	s_waitcnt vmcnt(35)
	v_cvt_pk_bf16_f32 v22, v136, v137
	v_cvt_pk_bf16_f32 v23, v138, v139
	v_and_b32_e32 v125, 0xffff0000, v22
	v_and_b32_e32 v127, 0xffff0000, v23
	v_lshlrev_b32_e32 v124, 16, v22
	v_lshlrev_b32_e32 v126, 16, v23
	v_mul_f32_e32 v125, v125, v125
	v_mul_f32_e32 v127, v127, v127
	v_fmac_f32_e32 v125, v124, v124
	v_fmac_f32_e32 v127, v126, v126
	v_add_f32_e32 v124, v125, v127
	v_add_f32_e32 v124, v24, v124
	s_nop 1
	v_add_f32_dpp v125, v124, v124 quad_perm:[1,0,3,2] row_mask:0xf bank_mask:0xf
	s_nop 1
	v_add_f32_dpp v124, v125, v125 quad_perm:[2,3,0,1] row_mask:0xf bank_mask:0xf
	s_nop 1
	v_add_f32_dpp v125, v124, v124 row_half_mirror row_mask:0xf bank_mask:0xf
	s_nop 1
	v_add_f32_dpp v124, v125, v125 row_ror:8 row_mask:0xf bank_mask:0xf
	v_mov_b32_e32 v125, v124
	s_nop 1
	v_permlane16_swap_b32_e32 v125, v124
	v_add_f32_e32 v124, v125, v124
	v_mov_b32_e32 v125, v124
	s_nop 1
	v_permlane32_swap_b32_e32 v125, v124
	v_add_f32_e32 v124, v125, v124
	global_store_dwordx2 v[20:21], v[22:23], off offset:1536
	s_and_saveexec_b64 s[12:13], s[0:1]
	v_lshl_add_u64 v[126:127], s[46:47], 0, v[2:3]
	v_cndmask_b32_e64 v124, 0, v124, s[4:5]
	global_store_dword v[126:127], v124, off
	s_or_b64 exec, exec, s[12:13]
	v_lshl_add_u64 v[2:3], v[2:3], 0, s[6:7]
	v_lshl_add_u64 v[4:5], v[4:5], 0, s[8:9]
	v_lshl_add_u64 v[20:21], s[46:47], 0, v[4:5]
	v_add_co_u32_e32 v20, vcc, 0xe200000, v20
	s_waitcnt vmcnt(36)
	v_cvt_pk_bf16_f32 v22, v140, v141
	v_addc_co_u32_e32 v21, vcc, 0, v21, vcc
	v_cvt_pk_bf16_f32 v23, v142, v143
	global_store_dwordx2 v[20:21], v[22:23], off
	v_lshlrev_b32_e32 v28, 16, v22
	v_and_b32_e32 v22, 0xffff0000, v22
	v_lshlrev_b32_e32 v29, 16, v23
	v_and_b32_e32 v23, 0xffff0000, v23
	v_mul_f32_e32 v22, v22, v22
	v_mul_f32_e32 v23, v23, v23
	v_fmac_f32_e32 v22, v28, v28
	v_fmac_f32_e32 v23, v29, v29
	v_add_f32_e32 v22, v22, v23
	s_waitcnt vmcnt(36)
	v_cvt_pk_bf16_f32 v24, v144, v145
	v_cvt_pk_bf16_f32 v25, v146, v147
	global_store_dwordx2 v[20:21], v[24:25], off offset:512
	v_lshlrev_b32_e32 v23, 16, v24
	v_and_b32_e32 v24, 0xffff0000, v24
	v_lshlrev_b32_e32 v28, 16, v25
	v_and_b32_e32 v25, 0xffff0000, v25
	v_mul_f32_e32 v24, v24, v24
	v_mul_f32_e32 v25, v25, v25
	v_fmac_f32_e32 v24, v23, v23
	v_fmac_f32_e32 v25, v28, v28
	v_add_f32_e32 v23, v24, v25
	v_add_f32_e32 v22, v22, v23
	s_waitcnt vmcnt(36)
	v_cvt_pk_bf16_f32 v26, v148, v149
	v_cvt_pk_bf16_f32 v27, v150, v151
	global_store_dwordx2 v[20:21], v[26:27], off offset:1024
	v_lshlrev_b32_e32 v23, 16, v26
	v_and_b32_e32 v24, 0xffff0000, v26
	v_and_b32_e32 v26, 0xffff0000, v27
	v_lshlrev_b32_e32 v25, 16, v27
	v_mul_f32_e32 v24, v24, v24
	v_mul_f32_e32 v26, v26, v26
	v_fmac_f32_e32 v24, v23, v23
	v_fmac_f32_e32 v26, v25, v25
	v_add_f32_e32 v23, v24, v26
	v_add_f32_e32 v24, v22, v23
	s_waitcnt vmcnt(36)
	v_cvt_pk_bf16_f32 v22, v152, v153
	v_cvt_pk_bf16_f32 v23, v154, v155
	v_and_b32_e32 v141, 0xffff0000, v22
	v_and_b32_e32 v143, 0xffff0000, v23
	v_lshlrev_b32_e32 v140, 16, v22
	v_lshlrev_b32_e32 v142, 16, v23
	v_mul_f32_e32 v141, v141, v141
	v_mul_f32_e32 v143, v143, v143
	v_fmac_f32_e32 v141, v140, v140
	v_fmac_f32_e32 v143, v142, v142
	v_add_f32_e32 v140, v141, v143
	v_add_f32_e32 v140, v24, v140
	s_nop 1
	v_add_f32_dpp v141, v140, v140 quad_perm:[1,0,3,2] row_mask:0xf bank_mask:0xf
	s_nop 1
	v_add_f32_dpp v140, v141, v141 quad_perm:[2,3,0,1] row_mask:0xf bank_mask:0xf
	s_nop 1
	v_add_f32_dpp v141, v140, v140 row_half_mirror row_mask:0xf bank_mask:0xf
	s_nop 1
	v_add_f32_dpp v140, v141, v141 row_ror:8 row_mask:0xf bank_mask:0xf
	v_mov_b32_e32 v141, v140
	s_nop 1
	v_permlane16_swap_b32_e32 v141, v140
	v_add_f32_e32 v140, v141, v140
	v_mov_b32_e32 v141, v140
	s_nop 1
	v_permlane32_swap_b32_e32 v141, v140
	v_add_f32_e32 v140, v141, v140
	global_store_dwordx2 v[20:21], v[22:23], off offset:1536
	s_and_saveexec_b64 s[12:13], s[0:1]
	v_lshl_add_u64 v[142:143], s[46:47], 0, v[2:3]
	v_cndmask_b32_e64 v140, 0, v140, s[4:5]
	global_store_dword v[142:143], v140, off
	s_or_b64 exec, exec, s[12:13]
	v_lshl_add_u64 v[2:3], v[2:3], 0, s[6:7]
	v_lshl_add_u64 v[4:5], v[4:5], 0, s[8:9]
	v_lshl_add_u64 v[20:21], s[46:47], 0, v[4:5]
	v_add_co_u32_e32 v20, vcc, 0xe200000, v20
	s_waitcnt vmcnt(37)
	v_cvt_pk_bf16_f32 v22, v156, v157
	v_addc_co_u32_e32 v21, vcc, 0, v21, vcc
	v_cvt_pk_bf16_f32 v23, v158, v159
	global_store_dwordx2 v[20:21], v[22:23], off
	v_lshlrev_b32_e32 v28, 16, v22
	v_and_b32_e32 v22, 0xffff0000, v22
	v_lshlrev_b32_e32 v29, 16, v23
	v_and_b32_e32 v23, 0xffff0000, v23
	v_mul_f32_e32 v22, v22, v22
	v_mul_f32_e32 v23, v23, v23
	v_fmac_f32_e32 v22, v28, v28
	v_fmac_f32_e32 v23, v29, v29
	v_add_f32_e32 v22, v22, v23
	s_waitcnt vmcnt(37)
	v_cvt_pk_bf16_f32 v24, v160, v161
	v_cvt_pk_bf16_f32 v25, v162, v163
	global_store_dwordx2 v[20:21], v[24:25], off offset:512
	v_lshlrev_b32_e32 v23, 16, v24
	v_and_b32_e32 v24, 0xffff0000, v24
	v_lshlrev_b32_e32 v28, 16, v25
	v_and_b32_e32 v25, 0xffff0000, v25
	v_mul_f32_e32 v24, v24, v24
	v_mul_f32_e32 v25, v25, v25
	v_fmac_f32_e32 v24, v23, v23
	v_fmac_f32_e32 v25, v28, v28
	v_add_f32_e32 v23, v24, v25
	v_add_f32_e32 v22, v22, v23
	s_waitcnt vmcnt(37)
	v_cvt_pk_bf16_f32 v26, v164, v165
	v_cvt_pk_bf16_f32 v27, v166, v167
	global_store_dwordx2 v[20:21], v[26:27], off offset:1024
	v_lshlrev_b32_e32 v23, 16, v26
	v_and_b32_e32 v24, 0xffff0000, v26
	v_and_b32_e32 v26, 0xffff0000, v27
	v_lshlrev_b32_e32 v25, 16, v27
	v_mul_f32_e32 v24, v24, v24
	v_mul_f32_e32 v26, v26, v26
	v_fmac_f32_e32 v24, v23, v23
	v_fmac_f32_e32 v26, v25, v25
	v_add_f32_e32 v23, v24, v26
	v_add_f32_e32 v24, v22, v23
	s_waitcnt vmcnt(37)
	v_cvt_pk_bf16_f32 v22, v168, v169
	v_cvt_pk_bf16_f32 v23, v170, v171
	v_and_b32_e32 v157, 0xffff0000, v22
	v_and_b32_e32 v159, 0xffff0000, v23
	v_lshlrev_b32_e32 v156, 16, v22
	v_lshlrev_b32_e32 v158, 16, v23
	v_mul_f32_e32 v157, v157, v157
	v_mul_f32_e32 v159, v159, v159
	v_fmac_f32_e32 v157, v156, v156
	v_fmac_f32_e32 v159, v158, v158
	v_add_f32_e32 v156, v157, v159
	v_add_f32_e32 v156, v24, v156
	s_nop 1
	v_add_f32_dpp v157, v156, v156 quad_perm:[1,0,3,2] row_mask:0xf bank_mask:0xf
	s_nop 1
	v_add_f32_dpp v156, v157, v157 quad_perm:[2,3,0,1] row_mask:0xf bank_mask:0xf
	s_nop 1
	v_add_f32_dpp v157, v156, v156 row_half_mirror row_mask:0xf bank_mask:0xf
	s_nop 1
	v_add_f32_dpp v156, v157, v157 row_ror:8 row_mask:0xf bank_mask:0xf
	v_mov_b32_e32 v157, v156
	s_nop 1
	v_permlane16_swap_b32_e32 v157, v156
	v_add_f32_e32 v156, v157, v156
	v_mov_b32_e32 v157, v156
	s_nop 1
	v_permlane32_swap_b32_e32 v157, v156
	v_add_f32_e32 v156, v157, v156
	global_store_dwordx2 v[20:21], v[22:23], off offset:1536
	s_and_saveexec_b64 s[12:13], s[0:1]
	v_lshl_add_u64 v[158:159], s[46:47], 0, v[2:3]
	v_cndmask_b32_e64 v156, 0, v156, s[4:5]
	global_store_dword v[158:159], v156, off
	s_or_b64 exec, exec, s[12:13]
	v_lshl_add_u64 v[2:3], v[2:3], 0, s[6:7]
	v_lshl_add_u64 v[4:5], v[4:5], 0, s[8:9]
	v_lshl_add_u64 v[20:21], s[46:47], 0, v[4:5]
	v_add_co_u32_e32 v20, vcc, 0xe200000, v20
	s_waitcnt vmcnt(38)
	v_cvt_pk_bf16_f32 v22, v172, v173
	v_addc_co_u32_e32 v21, vcc, 0, v21, vcc
	v_cvt_pk_bf16_f32 v23, v174, v175
	global_store_dwordx2 v[20:21], v[22:23], off
	v_lshlrev_b32_e32 v28, 16, v22
	v_and_b32_e32 v22, 0xffff0000, v22
	v_lshlrev_b32_e32 v29, 16, v23
	v_and_b32_e32 v23, 0xffff0000, v23
	v_mul_f32_e32 v22, v22, v22
	v_mul_f32_e32 v23, v23, v23
	v_fmac_f32_e32 v22, v28, v28
	v_fmac_f32_e32 v23, v29, v29
	v_add_f32_e32 v22, v22, v23
	s_waitcnt vmcnt(38)
	v_cvt_pk_bf16_f32 v24, v176, v177
	v_cvt_pk_bf16_f32 v25, v178, v179
	global_store_dwordx2 v[20:21], v[24:25], off offset:512
	v_lshlrev_b32_e32 v23, 16, v24
	v_and_b32_e32 v24, 0xffff0000, v24
	v_lshlrev_b32_e32 v28, 16, v25
	v_and_b32_e32 v25, 0xffff0000, v25
	v_mul_f32_e32 v24, v24, v24
	v_mul_f32_e32 v25, v25, v25
	v_fmac_f32_e32 v24, v23, v23
	v_fmac_f32_e32 v25, v28, v28
	v_add_f32_e32 v23, v24, v25
	v_add_f32_e32 v22, v22, v23
	s_waitcnt vmcnt(38)
	v_cvt_pk_bf16_f32 v26, v180, v181
	v_cvt_pk_bf16_f32 v27, v182, v183
	global_store_dwordx2 v[20:21], v[26:27], off offset:1024
	v_lshlrev_b32_e32 v23, 16, v26
	v_and_b32_e32 v24, 0xffff0000, v26
	v_and_b32_e32 v26, 0xffff0000, v27
	v_lshlrev_b32_e32 v25, 16, v27
	v_mul_f32_e32 v24, v24, v24
	v_mul_f32_e32 v26, v26, v26
	v_fmac_f32_e32 v24, v23, v23
	v_fmac_f32_e32 v26, v25, v25
	v_add_f32_e32 v23, v24, v26
	v_add_f32_e32 v24, v22, v23
	s_waitcnt vmcnt(38)
	v_cvt_pk_bf16_f32 v22, v184, v185
	v_cvt_pk_bf16_f32 v23, v186, v187
	v_and_b32_e32 v173, 0xffff0000, v22
	v_and_b32_e32 v175, 0xffff0000, v23
	v_lshlrev_b32_e32 v172, 16, v22
	v_lshlrev_b32_e32 v174, 16, v23
	v_mul_f32_e32 v173, v173, v173
	v_mul_f32_e32 v175, v175, v175
	v_fmac_f32_e32 v173, v172, v172
	v_fmac_f32_e32 v175, v174, v174
	v_add_f32_e32 v172, v173, v175
	v_add_f32_e32 v172, v24, v172
	s_nop 1
	v_add_f32_dpp v173, v172, v172 quad_perm:[1,0,3,2] row_mask:0xf bank_mask:0xf
	s_nop 1
	v_add_f32_dpp v172, v173, v173 quad_perm:[2,3,0,1] row_mask:0xf bank_mask:0xf
	s_nop 1
	v_add_f32_dpp v173, v172, v172 row_half_mirror row_mask:0xf bank_mask:0xf
	s_nop 1
	v_add_f32_dpp v172, v173, v173 row_ror:8 row_mask:0xf bank_mask:0xf
	v_mov_b32_e32 v173, v172
	s_nop 1
	v_permlane16_swap_b32_e32 v173, v172
	v_add_f32_e32 v172, v173, v172
	v_mov_b32_e32 v173, v172
	s_nop 1
	v_permlane32_swap_b32_e32 v173, v172
	v_add_f32_e32 v172, v173, v172
	global_store_dwordx2 v[20:21], v[22:23], off offset:1536
	s_and_saveexec_b64 s[12:13], s[0:1]
	v_lshl_add_u64 v[174:175], s[46:47], 0, v[2:3]
	v_cndmask_b32_e64 v172, 0, v172, s[4:5]
	global_store_dword v[174:175], v172, off
	s_or_b64 exec, exec, s[12:13]
	s_branch .LBB0_66
.Lx_generic:
	s_branch .LBB0_64
.LBB0_63:
	s_or_b64 exec, exec, s[12:13]
	s_add_i32 s3, s3, s40
	v_lshl_add_u64 v[2:3], v[2:3], 0, s[6:7]
	v_lshl_add_u64 v[4:5], v[4:5], 0, s[8:9]
	s_cmpk_gt_i32 s3, 0x3fff
	v_lshl_add_u64 v[6:7], v[6:7], 0, s[10:11]
	s_cbranch_scc1 .LBB0_66
